# sample-row LayerNorm: row read with sc1 loads after the arrival poll (no L1 invalidate), its four 16-B loads issued together
# baseline (speedup 1.0000x reference)
.LBB0_92:
	s_waitcnt lgkmcnt(0)
	s_nop 0
	s_nop 0

.LBB0_97:
	v_lshl_add_u64 v[72:73], s[74:75], 0, v[54:55]
	v_add_co_u32_e32 v32, vcc, 0x2df41000, v72
	s_mov_b32 s8, 0x11021000
	s_nop 0
	v_addc_co_u32_e32 v33, vcc, 0, v73, vcc
	global_load_dwordx4 v[60:63], v[32:33], off sc1
	global_load_dwordx4 v[40:43], v[32:33], off offset:1024 sc1
	global_load_dwordx4 v[36:39], v[32:33], off offset:2048 sc1
	global_load_dwordx4 v[32:35], v[32:33], off offset:3072 sc1
	v_add_u32_e32 v51, 8, v51
	v_lshl_add_u64 v[54:55], v[54:55], 0, s[10:11]
	s_waitcnt vmcnt(3)
	v_mov_b32_e32 v212, v61
	v_mov_b32_e32 v213, v62
	v_mov_b32_e32 v214, v60
	v_mov_b32_e32 v215, v63
	v_pk_add_f32 v[212:213], v[212:213], v[214:215]
	s_waitcnt vmcnt(2)
	v_mov_b32_e32 v214, v40
	v_add_f32_e32 v212, v212, v213
	v_add_f32_e32 v68, 0, v212
	v_mov_b32_e32 v212, v41
	v_mov_b32_e32 v213, v42
	v_mov_b32_e32 v215, v43
	v_pk_add_f32 v[212:213], v[212:213], v[214:215]
	s_nop 0
	v_pk_add_f32 v[70:71], v[212:213], v[212:213] op_sel:[0,1] op_sel_hi:[1,0]
	s_nop 0
	s_waitcnt vmcnt(1)
	v_add_f32_e32 v74, v36, v37
	v_add_f32_e32 v76, v38, v39
	s_waitcnt vmcnt(0)
	v_mov_b32_e32 v69, v32
	v_mov_b32_e32 v71, v33
	v_mov_b32_e32 v75, v34
	v_mov_b32_e32 v77, v35
	v_pk_add_f32 v[68:69], v[68:69], v[70:71]
	v_pk_add_f32 v[70:71], v[74:75], v[76:77]
	s_nop 0
	v_pk_add_f32 v[68:69], v[68:69], v[70:71]
	s_nop 0
	v_add_f32_e32 v58, v68, v69
	ds_bpermute_b32 v68, v53, v58
	s_waitcnt lgkmcnt(0)
	v_add_f32_e32 v58, v58, v68
	ds_bpermute_b32 v68, v59, v58
	s_waitcnt lgkmcnt(0)
	v_add_f32_e32 v58, v58, v68
	ds_bpermute_b32 v68, v64, v58
	s_waitcnt lgkmcnt(0)
	v_add_f32_e32 v58, v58, v68
	ds_bpermute_b32 v68, v65, v58
	s_waitcnt lgkmcnt(0)
	v_add_f32_e32 v58, v58, v68
	ds_bpermute_b32 v68, v66, v58
	s_waitcnt lgkmcnt(0)
	v_add_f32_e32 v58, v58, v68
	ds_bpermute_b32 v68, v67, v58
	s_waitcnt lgkmcnt(0)
	v_add_f32_e32 v78, v58, v68
	v_fmamk_f32 v61, v78, 0xba800000, v61
	v_fmamk_f32 v60, v78, 0xba800000, v60
	v_fmamk_f32 v63, v78, 0xba800000, v63
	v_fmac_f32_e32 v62, 0xba800000, v78
	v_pk_mul_f32 v[68:69], v[62:63], v[62:63]
	v_pk_mul_f32 v[70:71], v[60:61], v[60:61]
	v_fmamk_f32 v41, v78, 0xba800000, v41
	v_pk_mov_b32 v[74:75], v[70:71], v[68:69] op_sel:[1,0]
	v_mov_b32_e32 v71, v69
	v_fmamk_f32 v40, v78, 0xba800000, v40
	v_fmamk_f32 v43, v78, 0xba800000, v43
	v_fmac_f32_e32 v42, 0xba800000, v78
	v_pk_add_f32 v[68:69], v[74:75], v[70:71]
	v_pk_mul_f32 v[70:71], v[42:43], v[42:43]
	v_pk_mul_f32 v[74:75], v[40:41], v[40:41]
	v_fmamk_f32 v36, v78, 0xba800000, v36
	v_pk_mov_b32 v[76:77], v[74:75], v[70:71] op_sel:[1,0]
	v_mov_b32_e32 v75, v71
	v_fmamk_f32 v37, v78, 0xba800000, v37
	v_fmac_f32_e32 v38, 0xba800000, v78
	v_mul_f32_e32 v58, v36, v36
	v_pk_add_f32 v[70:71], v[76:77], v[74:75]
	v_fmamk_f32 v39, v78, 0xba800000, v39
	v_pk_fma_f32 v[74:75], v[36:37], v[36:37], v[58:59] op_sel_hi:[1,1,0]
	v_mul_f32_e32 v58, v38, v38
	v_pk_add_f32 v[68:69], v[68:69], v[68:69] op_sel_hi:[0,1]
	v_pk_add_f32 v[70:71], v[70:71], v[70:71] op_sel_hi:[0,1]
	v_pk_fma_f32 v[76:77], v[38:39], v[38:39], v[58:59] op_sel_hi:[1,1,0]
	v_fmamk_f32 v35, v78, 0xba800000, v35
	v_fmamk_f32 v34, v78, 0xba800000, v34
	v_fmamk_f32 v33, v78, 0xba800000, v33
	v_fmac_f32_e32 v32, 0xba800000, v78
	v_mul_f32_e32 v74, v32, v32
	v_mul_f32_e32 v76, v33, v33
	v_mul_f32_e32 v68, v34, v34
	v_mul_f32_e32 v70, v35, v35
	v_pk_add_f32 v[74:75], v[74:75], v[76:77]
	v_pk_add_f32 v[68:69], v[68:69], v[70:71]
	s_nop 0
	v_pk_add_f32 v[68:69], v[74:75], v[68:69]
	s_nop 0
	v_add_f32_e32 v58, v68, v69
	ds_bpermute_b32 v68, v53, v58
	s_waitcnt lgkmcnt(0)
	v_add_f32_e32 v58, v58, v68
	ds_bpermute_b32 v68, v59, v58
	s_waitcnt lgkmcnt(0)
	v_add_f32_e32 v58, v58, v68
	ds_bpermute_b32 v68, v64, v58
	s_waitcnt lgkmcnt(0)
	v_add_f32_e32 v58, v58, v68
	ds_bpermute_b32 v68, v65, v58
	s_waitcnt lgkmcnt(0)
	v_add_f32_e32 v58, v58, v68
	ds_bpermute_b32 v68, v66, v58
	s_waitcnt lgkmcnt(0)
	v_add_f32_e32 v58, v58, v68
	ds_bpermute_b32 v68, v67, v58
	s_waitcnt lgkmcnt(0)
	v_add_f32_e32 v58, v58, v68
	v_fmamk_f32 v58, v58, 0x3a800000, v198
	v_cmp_gt_f32_e32 vcc, s86, v58
	v_mul_f32_e32 v68, 0x4b800000, v58
	s_nop 0
	v_cndmask_b32_e32 v58, v58, v68, vcc
	v_rsq_f32_e32 v58, v58
	s_nop 0
	v_mul_f32_e32 v68, 0x45800000, v58
	v_cndmask_b32_e32 v58, v58, v68, vcc
	v_pk_mul_f32 v[60:61], v[60:61], v[58:59] op_sel_hi:[1,0]
	v_pk_mul_f32 v[62:63], v[62:63], v[58:59] op_sel_hi:[1,0]
	v_pk_fma_f32 v[68:69], v[0:1], v[60:61], v[8:9]
	v_add_co_u32_e32 v60, vcc, s50, v72
	v_pk_fma_f32 v[70:71], v[2:3], v[62:63], v[10:11]
	s_nop 0
	v_addc_co_u32_e32 v61, vcc, 0, v73, vcc
	global_store_dwordx4 v[60:61], v[68:71], off
	v_cvt_pk_bf16_f32 v62, v68, v69
	v_pk_mul_f32 v[40:41], v[40:41], v[58:59] op_sel_hi:[1,0]
	v_pk_mul_f32 v[42:43], v[42:43], v[58:59] op_sel_hi:[1,0]
	v_lshl_add_u64 v[68:69], s[74:75], 0, v[56:57]
	v_add_co_u32_e32 v68, vcc, s8, v68
	v_pk_mul_f32 v[36:37], v[36:37], v[58:59] op_sel_hi:[1,0]
	s_nop 0
	v_addc_co_u32_e32 v69, vcc, 0, v69, vcc
	v_pk_mul_f32 v[38:39], v[38:39], v[58:59] op_sel_hi:[1,0]
	v_pk_mul_f32 v[32:33], v[32:33], v[58:59] op_sel_hi:[1,0]
	v_pk_mul_f32 v[34:35], v[34:35], v[58:59] op_sel_hi:[1,0]
	v_cmp_lt_i32_e32 vcc, s7, v51
	v_pk_fma_f32 v[42:43], v[6:7], v[42:43], v[14:15]
	v_pk_fma_f32 v[40:41], v[4:5], v[40:41], v[12:13]
	v_pk_fma_f32 v[38:39], v[18:19], v[38:39], v[26:27]
	v_pk_fma_f32 v[36:37], v[16:17], v[36:37], v[24:25]
	v_pk_fma_f32 v[34:35], v[22:23], v[34:35], v[30:31]
	v_pk_fma_f32 v[32:33], v[20:21], v[32:33], v[28:29]
	v_lshl_add_u64 v[56:57], v[56:57], 0, s[42:43]
	s_or_b64 s[4:5], vcc, s[4:5]
	v_cvt_pk_bf16_f32 v63, v70, v71
	global_store_dwordx2 v[68:69], v[62:63], off
	global_store_dwordx4 v[60:61], v[40:43], off offset:1024
	s_nop 1
	v_cvt_pk_bf16_f32 v40, v40, v41
	v_cvt_pk_bf16_f32 v41, v42, v43
	global_store_dwordx2 v[68:69], v[40:41], off offset:512
	global_store_dwordx4 v[60:61], v[36:39], off offset:2048
	s_nop 1
	v_cvt_pk_bf16_f32 v36, v36, v37
	v_cvt_pk_bf16_f32 v37, v38, v39
	global_store_dwordx2 v[68:69], v[36:37], off offset:1024
	global_store_dwordx4 v[60:61], v[32:35], off offset:3072
	s_nop 1
	v_cvt_pk_bf16_f32 v32, v32, v33
	v_cvt_pk_bf16_f32 v33, v34, v35
	global_store_dwordx2 v[68:69], v[32:33], off offset:1536
	s_andn2_b64 exec, exec, s[4:5]
	s_cbranch_execnz .LBB0_97
	s_branch .LBB0_94

.LBB0_521:
	v_lshl_add_u64 v[68:69], s[74:75], 0, v[58:59]
	v_add_co_u32_e32 v32, vcc, 0x2df41000, v68
	s_nop 1
	v_addc_co_u32_e32 v33, vcc, 0, v69, vcc
	global_load_dwordx4 v[44:47], v[32:33], off sc1
	global_load_dwordx4 v[40:43], v[32:33], off offset:1024 sc1
	global_load_dwordx4 v[36:39], v[32:33], off offset:2048 sc1
	global_load_dwordx4 v[32:35], v[32:33], off offset:3072 sc1
	s_waitcnt vmcnt(3)
	v_mov_b32_e32 v212, v45
	v_mov_b32_e32 v213, v46
	v_mov_b32_e32 v214, v44
	v_mov_b32_e32 v215, v47
	v_pk_add_f32 v[212:213], v[212:213], v[214:215]
	s_waitcnt vmcnt(2)
	v_mov_b32_e32 v214, v40
	v_add_f32_e32 v212, v212, v213
	v_add_f32_e32 v62, 0, v212
	v_mov_b32_e32 v212, v41
	v_mov_b32_e32 v213, v42
	v_mov_b32_e32 v215, v43
	v_pk_add_f32 v[212:213], v[212:213], v[214:215]
	s_nop 0
	v_pk_add_f32 v[64:65], v[212:213], v[212:213] op_sel:[0,1] op_sel_hi:[1,0]
	s_nop 0
	s_waitcnt vmcnt(1)
	v_add_f32_e32 v66, v36, v37
	v_add_f32_e32 v70, v38, v39
	s_waitcnt vmcnt(0)
	v_mov_b32_e32 v63, v32
	v_mov_b32_e32 v65, v33
	v_mov_b32_e32 v67, v34
	v_mov_b32_e32 v71, v35
	v_pk_add_f32 v[62:63], v[62:63], v[64:65]
	v_pk_add_f32 v[64:65], v[66:67], v[70:71]
	s_nop 0
	v_pk_add_f32 v[62:63], v[62:63], v[64:65]
	s_nop 0
	v_add_f32_e32 v62, v62, v63
	ds_bpermute_b32 v63, v57, v62
	s_waitcnt lgkmcnt(0)
	v_add_f32_e32 v62, v62, v63
	ds_bpermute_b32 v63, v74, v62
	s_waitcnt lgkmcnt(0)
	v_add_f32_e32 v62, v62, v63
	ds_bpermute_b32 v63, v75, v62
	s_waitcnt lgkmcnt(0)
	v_add_f32_e32 v62, v62, v63
	ds_bpermute_b32 v63, v76, v62
	s_waitcnt lgkmcnt(0)
	v_add_f32_e32 v62, v62, v63
	ds_bpermute_b32 v63, v77, v62
	s_waitcnt lgkmcnt(0)
	v_add_f32_e32 v62, v62, v63
	ds_bpermute_b32 v63, v78, v62
	s_waitcnt lgkmcnt(0)
	v_add_f32_e32 v79, v62, v63
	v_fmamk_f32 v45, v79, 0xba800000, v45
	v_fmamk_f32 v44, v79, 0xba800000, v44
	v_fmamk_f32 v47, v79, 0xba800000, v47
	v_fmac_f32_e32 v46, 0xba800000, v79
	v_pk_mul_f32 v[62:63], v[46:47], v[46:47]
	v_pk_mul_f32 v[64:65], v[44:45], v[44:45]
	v_fmamk_f32 v41, v79, 0xba800000, v41
	v_pk_mov_b32 v[66:67], v[64:65], v[62:63] op_sel:[1,0]
	v_mov_b32_e32 v65, v63
	v_pk_add_f32 v[62:63], v[66:67], v[64:65]
	v_fmamk_f32 v67, v79, 0xba800000, v43
	v_fmamk_f32 v66, v79, 0xba800000, v42
	v_fmac_f32_e32 v40, 0xba800000, v79
	v_pk_add_f32 v[70:71], v[62:63], v[62:63] op_sel_hi:[0,1]
	v_pk_mul_f32 v[42:43], v[66:67], v[66:67]
	v_pk_mul_f32 v[62:63], v[40:41], v[40:41]
	v_fmac_f32_e32 v36, 0xba800000, v79
	v_pk_mov_b32 v[64:65], v[62:63], v[42:43] op_sel:[1,0]
	v_mov_b32_e32 v63, v43
	v_pk_add_f32 v[42:43], v[64:65], v[62:63]
	v_fmamk_f32 v64, v79, 0xba800000, v38
	v_fmamk_f32 v37, v79, 0xba800000, v37
	v_mul_f32_e32 v38, v36, v36
	v_fmamk_f32 v65, v79, 0xba800000, v39
	v_pk_fma_f32 v[38:39], v[36:37], v[36:37], v[38:39] op_sel_hi:[1,1,0]
	v_pk_add_f32 v[42:43], v[42:43], v[42:43] op_sel_hi:[0,1]
	v_mul_f32_e32 v38, v64, v64
	v_pk_fma_f32 v[72:73], v[64:65], v[64:65], v[38:39] op_sel_hi:[1,1,0]
	v_fmamk_f32 v63, v79, 0xba800000, v35
	v_fmamk_f32 v62, v79, 0xba800000, v34
	v_fmamk_f32 v33, v79, 0xba800000, v33
	v_fmac_f32_e32 v32, 0xba800000, v79
	v_mul_f32_e32 v38, v32, v32
	v_mul_f32_e32 v72, v33, v33
	v_mul_f32_e32 v70, v62, v62
	v_mul_f32_e32 v42, v63, v63
	v_pk_add_f32 v[34:35], v[38:39], v[72:73]
	v_pk_add_f32 v[38:39], v[70:71], v[42:43]
	v_lshl_add_u64 v[72:73], s[72:73], 0, v[58:59]
	v_pk_add_f32 v[34:35], v[34:35], v[38:39]
	s_nop 0
	v_add_f32_e32 v34, v34, v35
	ds_bpermute_b32 v35, v57, v34
	s_waitcnt lgkmcnt(0)
	v_add_f32_e32 v34, v34, v35
	ds_bpermute_b32 v35, v74, v34
	s_waitcnt lgkmcnt(0)
	v_add_f32_e32 v34, v34, v35
	ds_bpermute_b32 v35, v75, v34
	s_waitcnt lgkmcnt(0)
	v_add_f32_e32 v34, v34, v35
	ds_bpermute_b32 v35, v76, v34
	s_waitcnt lgkmcnt(0)
	v_add_f32_e32 v34, v34, v35
	ds_bpermute_b32 v35, v77, v34
	s_waitcnt lgkmcnt(0)
	v_add_f32_e32 v34, v34, v35
	ds_bpermute_b32 v35, v78, v34
	s_waitcnt lgkmcnt(0)
	v_add_f32_e32 v34, v34, v35
	v_fmamk_f32 v34, v34, 0x3a800000, v198
	v_cmp_gt_f32_e32 vcc, s86, v34
	v_mul_f32_e32 v35, 0x4b800000, v34
	s_nop 0
	v_cndmask_b32_e32 v34, v34, v35, vcc
	v_rsq_f32_e32 v34, v34
	s_nop 0
	v_mul_f32_e32 v35, 0x45800000, v34
	v_cndmask_b32_e32 v70, v34, v35, vcc
	v_pk_mul_f32 v[38:39], v[46:47], v[70:71] op_sel_hi:[1,0]
	v_add_co_u32_e32 v46, vcc, s50, v68
	v_pk_mul_f32 v[34:35], v[44:45], v[70:71] op_sel_hi:[1,0]
	s_nop 0
	v_addc_co_u32_e32 v47, vcc, 0, v69, vcc
	v_lshl_add_u64 v[68:69], s[74:75], 0, v[60:61]
	v_pk_fma_f32 v[44:45], v[2:3], v[38:39], v[10:11]
	v_add_co_u32_e32 v38, vcc, 0x11021000, v68
	v_pk_fma_f32 v[42:43], v[0:1], v[34:35], v[8:9]
	s_nop 0
	v_addc_co_u32_e32 v39, vcc, 0, v69, vcc
	v_cvt_pk_bf16_f32 v34, v42, v43
	global_store_dwordx4 v[46:47], v[42:45], off
	v_cvt_pk_bf16_f32 v35, v44, v45
	global_store_dwordx2 v[38:39], v[34:35], off
	v_cndmask_b32_e64 v34, 0, 1, s[20:21]
	v_cmp_ne_u32_e64 s[2:3], 1, v34
	s_andn2_b64 vcc, exec, s[20:21]
	s_cbranch_vccnz .LBB0_523
	global_store_dwordx4 v[72:73], v[42:45], off
